# S group step: six K fragments in flight (P registers double as K fragment buffers), V fragments of dim blocks 2,3 read into the freed score registers before the PV MFMAs
# speedup vs baseline: 1.0370x; 1.0055x over previous
.LBB0_2164:
	s_or_b64 exec, exec, s[20:21]
	v_add_u32_e32 v38, v34, v35
	v_bcnt_u32_b32 v37, v37, 0
	v_add_u32_e32 v38, v38, v36
	v_add_u32_e32 v150, v38, v37
	v_mul_f32_e32 v38, v133, v146
	v_cmp_eq_u32_e32 vcc, 0, v150
	v_pk_mul_f32 v[82:83], v[38:39], v[18:19] op_sel_hi:[0,1]
	v_add_u32_e32 v215, 0x9000, v214
	v_pk_mul_f32 v[84:85], v[38:39], v[20:21] op_sel_hi:[0,1]
	v_add_u32_e32 v216, 0x9008, v214
	v_pk_mul_f32 v[86:87], v[38:39], v[22:23] op_sel_hi:[0,1]
	v_add_u32_e32 v217, 0x9020, v214
	v_pk_mul_f32 v[88:89], v[38:39], v[24:25] op_sel_hi:[0,1]
	v_add_u32_e32 v218, 0x9028, v214
	v_pk_mul_f32 v[90:91], v[38:39], v[26:27] op_sel_hi:[0,1]
	v_add_u32_e32 v219, 0x9040, v214
	v_pk_mul_f32 v[92:93], v[38:39], v[28:29] op_sel_hi:[0,1]
	v_add_u32_e32 v220, 0x9048, v214
	v_pk_mul_f32 v[94:95], v[38:39], v[30:31] op_sel_hi:[0,1]
	v_add_u32_e32 v221, 0x9060, v214
	v_pk_mul_f32 v[96:97], v[38:39], v[32:33] op_sel_hi:[0,1]
	v_add_u32_e32 v222, 0x9068, v214
	v_pk_mul_f32 v[134:135], v[38:39], v[2:3] op_sel_hi:[0,1]
	v_add_u32_e32 v223, 0x9080, v214
	v_pk_mul_f32 v[136:137], v[38:39], v[4:5] op_sel_hi:[0,1]
	v_add_u32_e32 v224, 0x9088, v214
	v_pk_mul_f32 v[138:139], v[38:39], v[6:7] op_sel_hi:[0,1]
	v_add_u32_e32 v225, 0x90a0, v214
	v_pk_mul_f32 v[140:141], v[38:39], v[8:9] op_sel_hi:[0,1]
	v_add_u32_e32 v226, 0x90a8, v214
	v_pk_mul_f32 v[142:143], v[38:39], v[10:11] op_sel_hi:[0,1]
	v_add_u32_e32 v227, 0x90c0, v214
	v_pk_mul_f32 v[144:145], v[38:39], v[12:13] op_sel_hi:[0,1]
	v_add_u32_e32 v228, 0x90c8, v214
	v_pk_mul_f32 v[146:147], v[38:39], v[14:15] op_sel_hi:[0,1]
	v_add_u32_e32 v229, 0x90e0, v214
	v_pk_mul_f32 v[148:149], v[38:39], v[16:17] op_sel_hi:[0,1]
	v_add_u32_e32 v230, 0x90e8, v214
	s_and_b64 vcc, exec, vcc
	s_lshl_b32 s24, s71, 19
	s_waitcnt lgkmcnt(0)
	s_barrier
	ds_write2_b32 v215, v82, v83 offset1:1
	ds_write2_b32 v216, v84, v85 offset1:1
	ds_write2_b32 v217, v86, v87 offset1:1
	ds_write2_b32 v218, v88, v89 offset1:1
	ds_write2_b32 v219, v90, v91 offset1:1
	ds_write2_b32 v220, v92, v93 offset1:1
	ds_write2_b32 v221, v94, v95 offset1:1
	ds_write2_b32 v222, v96, v97 offset1:1
	ds_write2_b32 v223, v134, v135 offset1:1
	ds_write2_b32 v224, v136, v137 offset1:1
	ds_write2_b32 v225, v138, v139 offset1:1
	ds_write2_b32 v226, v140, v141 offset1:1
	ds_write2_b32 v227, v142, v143 offset1:1
	ds_write2_b32 v228, v144, v145 offset1:1
	ds_write2_b32 v229, v146, v147 offset1:1
	ds_write2_b32 v230, v148, v149 offset1:1
	s_cbranch_vccnz .LBB0_2181
	s_lshl_b32 s96, s66, 12
	s_and_b32 s96, s96, 0x6000
	s_lshl_b32 s95, s66, 3
	s_and_b32 s95, s95, 8
	s_sub_i32 s94, 0x1ff0, s70
	s_mov_b32 s98, 0x1000
	s_mov_b32 s99, 0
	v_and_b32_e32 v40, 15, v166
	v_bfe_u32 v41, v166, 4, 2
	v_lshrrev_b32_e32 v42, 6, v166
	v_lshlrev_b32_e32 v36, 4, v42
	v_and_b32_e32 v37, 63, v166
	v_readfirstlane_b32 s86, v36
	s_lshr_b32 s86, s86, 2
	s_lshl_b32 s87, 12, s86
	s_lshl_b32 s86, 3, s86
	v_lshlrev_b32_e32 v37, 2, v37
	v_add_u32_e32 v37, 0x11200, v37
	ds_read_b32 v133, v37 offset:256
	ds_read_b32 v148, v37 offset:512
	v_mul_u32_u24_e32 v234, 0x90, v40
	v_lshl_add_u32 v234, v41, 4, v234
	v_bfe_u32 v43, v166, 3, 1
	v_lshl_add_u32 v43, v42, 2, v43
	v_add_u32_e32 v236, s94, v43
	v_lshlrev_b32_e32 v44, 2, v41
	v_sub_u32_e32 v239, v236, v44
	v_lshl_add_u32 v45, v42, 5, v40
	v_mul_u32_u24_e32 v45, 0x41, v45
	v_lshl_add_u32 v45, v41, 2, v45
	v_lshlrev_b32_e32 v45, 2, v45
	v_add_u32_e32 v237, 0x9000, v45
	v_add_u32_e32 v238, 0x1040, v237
	v_add_u32_e32 v46, s96, v236
	v_mov_b32_e32 v47, 0
	v_lshlrev_b64 v[46:47], 11, v[46:47]
	v_lshl_add_u64 v[46:47], s[42:43], 0, v[46:47]
	v_and_b32_e32 v48, 7, v166
	v_or_b32_e32 v48, s95, v48
	v_lshlrev_b32_e32 v48, 7, v48
	v_lshl_add_u32 v48, v41, 4, v48
	v_mov_b32_e32 v49, 0
	v_lshl_add_u64 v[46:47], v[46:47], 0, v[48:49]
	global_load_dwordx4 v[66:69], v[46:47], off
	global_load_dwordx4 v[70:73], v[46:47], off offset:64
	v_lshl_add_u64 v[48:49], v[46:47], 0, s[98:99]
	global_load_dwordx4 v[74:77], v[48:49], off
	global_load_dwordx4 v[78:81], v[48:49], off offset:64
	v_mov_b32_e32 v235, 0
	s_lshl_b32 s22, s24, 1
	v_readlane_b32 s20, v231, 14
	s_add_u32 s20, s20, s22
	v_readlane_b32 s21, v231, 10
	s_addc_u32 s21, s21, 0
	s_add_u32 s22, s52, s22
	s_addc_u32 s23, s53, 0
	v_add_u32_e32 v134, v128, v106
	v_add_u32_e32 v135, v128, v108
	v_readfirstlane_b32 s101, v150
	s_mov_b32 s25, 0
	s_waitcnt lgkmcnt(0)
	s_and_b32 s38, s25, 63
	v_readlane_b32 s32, v133, s38
	v_readlane_b32 s38, v148, s38
	s_bitcmp1_b32 s25, 6
	s_cselect_b32 s32, s38, s32
	s_lshl_b32 s32, s32, 13
	s_add_u32 s28, s20, s32
	s_addc_u32 s29, s21, 0
	s_add_u32 s82, s22, s32
	s_addc_u32 s83, s23, 0
	global_load_dwordx4 v[82:85], v134, s[28:29]
	global_load_dwordx4 v[86:89], v134, s[82:83]
	global_load_dwordx4 v[90:93], v135, s[28:29]
	global_load_dwordx4 v[94:97], v135, s[82:83]
	s_cmp_lt_u32 s101, 2
	s_cbranch_scc1 .Lsb16_pa
	s_mov_b32 s58, 1
	s_and_b32 s38, s58, 63
	v_readlane_b32 s32, v133, s38
	v_readlane_b32 s38, v148, s38
	s_bitcmp1_b32 s58, 6
	s_cselect_b32 s32, s38, s32
	s_lshl_b32 s32, s32, 13
	s_add_u32 s28, s20, s32
	s_addc_u32 s29, s21, 0
	s_add_u32 s82, s22, s32
	s_addc_u32 s83, s23, 0
	global_load_dwordx4 v[240:243], v134, s[28:29]
	global_load_dwordx4 v[244:247], v134, s[82:83]
	global_load_dwordx4 v[248:251], v135, s[28:29]
	global_load_dwordx4 v[252:255], v135, s[82:83]

.Lsb16_nost_0:
	s_and_b32 s38, s25, 63
	v_readlane_b32 s32, v136, s38
	v_readlane_b32 s38, v137, s38
	s_bitcmp1_b32 s25, 6
	s_cselect_b32 s77, s38, s32
	s_and_b32 s56, s77, s86
	s_and_b32 s57, s77, s87
	s_or_b32 s28, s56, s57
	s_cmp_eq_u32 s28, 0
	s_cbranch_scc1 .Lsb16_end_0
	s_and_b32 s38, s25, 63
	v_readlane_b32 s32, v133, s38
	v_readlane_b32 s38, v148, s38
	s_bitcmp1_b32 s25, 6
	s_cselect_b32 s76, s38, s32
	s_lshl_b32 s83, s76, 6
	v_subrev_u32_e32 v147, s83, v239
	s_cmp_eq_u32 s56, 0
	s_cbranch_scc1 .Lsb16_g1_0
	ds_read_b128 v[50:53], v234
	ds_read_b128 v[54:57], v234 offset:64
	ds_read_b128 v[58:61], v234 offset:2304
	ds_read_b128 v[62:65], v234 offset:2368
	ds_read_b128 v[138:141], v234 offset:4608
	ds_read_b128 v[142:145], v234 offset:4672
	v_subrev_u32_e32 v146, s94, v236
	v_lshrrev_b32_e64 v146, v146, s77
	v_and_b32_e32 v146, 1, v146
	v_cmp_ne_u32_e32 vcc, 0, v146
	s_nop 1
	v_cndmask_b32_e32 v146, v213, v100, vcc
	s_waitcnt lgkmcnt(5)
	v_mfma_f32_16x16x32_bf16 v[34:37], v[50:53], v[66:69], 0
	s_waitcnt lgkmcnt(4)
	v_mfma_f32_16x16x32_bf16 v[34:37], v[54:57], v[70:73], v[34:37]
	ds_read_b128 v[50:53], v234 offset:6912
	ds_read_b128 v[54:57], v234 offset:6976
	s_waitcnt lgkmcnt(5)
	v_mfma_f32_16x16x32_bf16 v[38:41], v[58:61], v[66:69], 0
	s_waitcnt lgkmcnt(4)
	v_mfma_f32_16x16x32_bf16 v[38:41], v[62:65], v[70:73], v[38:41]
	ds_read_b128 v[58:61], v234 offset:9216
	ds_read_b128 v[62:65], v234 offset:9280
	s_waitcnt lgkmcnt(5)
	v_mfma_f32_16x16x32_bf16 v[42:45], v[138:141], v[66:69], 0
	s_waitcnt lgkmcnt(4)
	v_mfma_f32_16x16x32_bf16 v[42:45], v[142:145], v[70:73], v[42:45]
	s_waitcnt lgkmcnt(3)
	v_mfma_f32_16x16x32_bf16 v[46:49], v[50:53], v[66:69], 0
	s_waitcnt lgkmcnt(2)
	v_mfma_f32_16x16x32_bf16 v[46:49], v[54:57], v[70:73], v[46:49]
	ds_read_b128 v[50:53], v234 offset:11520
	ds_read_b128 v[54:57], v234 offset:11584
	v_fma_f32 v34, v34, s48, v146
	v_fma_f32 v35, v35, s48, v146
	v_fma_f32 v36, v36, s48, v146
	v_fma_f32 v37, v37, s48, v146
	v_fma_f32 v38, v38, s48, v146
	v_fma_f32 v39, v39, s48, v146
	v_fma_f32 v40, v40, s48, v146
	v_fma_f32 v41, v41, s48, v146
	v_fma_f32 v42, v42, s48, v146
	v_fma_f32 v43, v43, s48, v146
	v_fma_f32 v44, v44, s48, v146
	v_fma_f32 v45, v45, s48, v146
	v_fma_f32 v46, v46, s48, v146
	v_fma_f32 v47, v47, s48, v146
	v_fma_f32 v48, v48, s48, v146
	v_fma_f32 v49, v49, s48, v146
	s_cmp_lg_u32 s76, s72
	s_cbranch_scc1 .Lsb16_nm0_0
	v_cmp_le_i32_e64 s[28:29], 0, v147
	s_nop 1
	v_cndmask_b32_e64 v34, v213, v34, s[28:29]
	v_cmp_le_i32_e64 s[28:29], 1, v147
	s_nop 1
	v_cndmask_b32_e64 v35, v213, v35, s[28:29]
	v_cmp_le_i32_e64 s[28:29], 2, v147
	s_nop 1
	v_cndmask_b32_e64 v36, v213, v36, s[28:29]
	v_cmp_le_i32_e64 s[28:29], 3, v147
	s_nop 1
	v_cndmask_b32_e64 v37, v213, v37, s[28:29]
	v_cmp_le_i32_e64 s[28:29], 16, v147
	s_nop 1
	v_cndmask_b32_e64 v38, v213, v38, s[28:29]
	v_cmp_le_i32_e64 s[28:29], 17, v147
	s_nop 1
	v_cndmask_b32_e64 v39, v213, v39, s[28:29]
	v_cmp_le_i32_e64 s[28:29], 18, v147
	s_nop 1
	v_cndmask_b32_e64 v40, v213, v40, s[28:29]
	v_cmp_le_i32_e64 s[28:29], 19, v147
	s_nop 1
	v_cndmask_b32_e64 v41, v213, v41, s[28:29]
	v_cmp_le_i32_e64 s[28:29], 32, v147
	s_nop 1
	v_cndmask_b32_e64 v42, v213, v42, s[28:29]
	v_cmp_le_i32_e64 s[28:29], 33, v147
	s_nop 1
	v_cndmask_b32_e64 v43, v213, v43, s[28:29]
	v_cmp_le_i32_e64 s[28:29], 34, v147
	s_nop 1
	v_cndmask_b32_e64 v44, v213, v44, s[28:29]
	v_cmp_le_i32_e64 s[28:29], 35, v147
	s_nop 1
	v_cndmask_b32_e64 v45, v213, v45, s[28:29]
	v_cmp_le_i32_e64 s[28:29], 48, v147
	s_nop 1
	v_cndmask_b32_e64 v46, v213, v46, s[28:29]
	v_cmp_le_i32_e64 s[28:29], 49, v147
	s_nop 1
	v_cndmask_b32_e64 v47, v213, v47, s[28:29]
	v_cmp_le_i32_e64 s[28:29], 50, v147
	s_nop 1
	v_cndmask_b32_e64 v48, v213, v48, s[28:29]
	v_cmp_le_i32_e64 s[28:29], 51, v147
	s_nop 1
	v_cndmask_b32_e64 v49, v213, v49, s[28:29]
.Lsb16_nm0_0:
	v_exp_f32_e32 v34, v34
	v_exp_f32_e32 v35, v35
	v_exp_f32_e32 v36, v36
	v_exp_f32_e32 v37, v37
	v_exp_f32_e32 v38, v38
	v_exp_f32_e32 v39, v39
	v_exp_f32_e32 v40, v40
	v_exp_f32_e32 v41, v41
	v_exp_f32_e32 v42, v42
	v_exp_f32_e32 v43, v43
	v_exp_f32_e32 v44, v44
	v_exp_f32_e32 v45, v45
	v_exp_f32_e32 v46, v46
	v_exp_f32_e32 v47, v47
	v_exp_f32_e32 v48, v48
	v_exp_f32_e32 v49, v49
	v_add_f32_e32 v138, v34, v35
	v_add_f32_e32 v139, v36, v37
	v_add_f32_e32 v140, v38, v39
	v_add_f32_e32 v141, v40, v41
	v_add_f32_e32 v138, v138, v42
	v_add_f32_e32 v139, v139, v43
	v_add_f32_e32 v140, v140, v44
	v_add_f32_e32 v141, v141, v45
	v_add_f32_e32 v138, v138, v46
	v_add_f32_e32 v139, v139, v47
	v_add_f32_e32 v140, v140, v48
	v_add_f32_e32 v141, v141, v49
	v_add_f32_e32 v138, v138, v139
	v_add_f32_e32 v140, v140, v141
	v_add_f32_e32 v138, v138, v140
	v_add_f32_e32 v129, v129, v138
	v_cvt_pk_bf16_f32 v138, v34, v35
	v_cvt_pk_bf16_f32 v139, v36, v37
	v_cvt_pk_bf16_f32 v140, v38, v39
	v_cvt_pk_bf16_f32 v141, v40, v41
	v_cvt_pk_bf16_f32 v142, v42, v43
	v_cvt_pk_bf16_f32 v143, v44, v45
	v_cvt_pk_bf16_f32 v144, v46, v47
	v_cvt_pk_bf16_f32 v145, v48, v49
	ds_read_b128 v[34:37], v234 offset:13824
	ds_read_b128 v[38:41], v234 offset:13888
	ds_read_b128 v[42:45], v234 offset:16128
	ds_read_b128 v[46:49], v234 offset:16192
	s_waitcnt lgkmcnt(7)
	v_mfma_f32_16x16x32_bf16 v[2:5], v[58:61], v[138:141], v[2:5]
	s_waitcnt lgkmcnt(6)
	v_mfma_f32_16x16x32_bf16 v[2:5], v[62:65], v[142:145], v[2:5]
	s_waitcnt lgkmcnt(5)
	v_mfma_f32_16x16x32_bf16 v[6:9], v[50:53], v[138:141], v[6:9]
	s_waitcnt lgkmcnt(4)
	v_mfma_f32_16x16x32_bf16 v[6:9], v[54:57], v[142:145], v[6:9]
	s_waitcnt lgkmcnt(3)
	v_mfma_f32_16x16x32_bf16 v[10:13], v[34:37], v[138:141], v[10:13]
	s_waitcnt lgkmcnt(2)
	v_mfma_f32_16x16x32_bf16 v[10:13], v[38:41], v[142:145], v[10:13]
	s_waitcnt lgkmcnt(1)
	v_mfma_f32_16x16x32_bf16 v[14:17], v[42:45], v[138:141], v[14:17]
	s_waitcnt lgkmcnt(0)
	v_mfma_f32_16x16x32_bf16 v[14:17], v[46:49], v[142:145], v[14:17]
.Lsb16_g1_0:
	s_cmp_eq_u32 s57, 0
	s_cbranch_scc1 .Lsb16_end_0
	ds_read_b128 v[50:53], v234
	ds_read_b128 v[54:57], v234 offset:64
	ds_read_b128 v[58:61], v234 offset:2304
	ds_read_b128 v[62:65], v234 offset:2368
	ds_read_b128 v[138:141], v234 offset:4608
	ds_read_b128 v[142:145], v234 offset:4672
	v_add_u32_e32 v147, 2, v147
	v_subrev_u32_e32 v146, s94, v236
	v_add_u32_e32 v146, 2, v146
	v_lshrrev_b32_e64 v146, v146, s77
	v_and_b32_e32 v146, 1, v146
	v_cmp_ne_u32_e32 vcc, 0, v146
	s_nop 1
	v_cndmask_b32_e32 v146, v213, v100, vcc
	s_waitcnt lgkmcnt(5)
	v_mfma_f32_16x16x32_bf16 v[34:37], v[50:53], v[74:77], 0
	s_waitcnt lgkmcnt(4)
	v_mfma_f32_16x16x32_bf16 v[34:37], v[54:57], v[78:81], v[34:37]
	ds_read_b128 v[50:53], v234 offset:6912
	ds_read_b128 v[54:57], v234 offset:6976
	s_waitcnt lgkmcnt(5)
	v_mfma_f32_16x16x32_bf16 v[38:41], v[58:61], v[74:77], 0
	s_waitcnt lgkmcnt(4)
	v_mfma_f32_16x16x32_bf16 v[38:41], v[62:65], v[78:81], v[38:41]
	ds_read_b128 v[58:61], v234 offset:9216
	ds_read_b128 v[62:65], v234 offset:9280
	s_waitcnt lgkmcnt(5)
	v_mfma_f32_16x16x32_bf16 v[42:45], v[138:141], v[74:77], 0
	s_waitcnt lgkmcnt(4)
	v_mfma_f32_16x16x32_bf16 v[42:45], v[142:145], v[78:81], v[42:45]
	s_waitcnt lgkmcnt(3)
	v_mfma_f32_16x16x32_bf16 v[46:49], v[50:53], v[74:77], 0
	s_waitcnt lgkmcnt(2)
	v_mfma_f32_16x16x32_bf16 v[46:49], v[54:57], v[78:81], v[46:49]
	ds_read_b128 v[50:53], v234 offset:11520
	ds_read_b128 v[54:57], v234 offset:11584
	v_fma_f32 v34, v34, s48, v146
	v_fma_f32 v35, v35, s48, v146
	v_fma_f32 v36, v36, s48, v146
	v_fma_f32 v37, v37, s48, v146
	v_fma_f32 v38, v38, s48, v146
	v_fma_f32 v39, v39, s48, v146
	v_fma_f32 v40, v40, s48, v146
	v_fma_f32 v41, v41, s48, v146
	v_fma_f32 v42, v42, s48, v146
	v_fma_f32 v43, v43, s48, v146
	v_fma_f32 v44, v44, s48, v146
	v_fma_f32 v45, v45, s48, v146
	v_fma_f32 v46, v46, s48, v146
	v_fma_f32 v47, v47, s48, v146
	v_fma_f32 v48, v48, s48, v146
	v_fma_f32 v49, v49, s48, v146
	s_cmp_lg_u32 s76, s72
	s_cbranch_scc1 .Lsb16_nm1_0
	v_cmp_le_i32_e64 s[28:29], 0, v147
	s_nop 1
	v_cndmask_b32_e64 v34, v213, v34, s[28:29]
	v_cmp_le_i32_e64 s[28:29], 1, v147
	s_nop 1
	v_cndmask_b32_e64 v35, v213, v35, s[28:29]
	v_cmp_le_i32_e64 s[28:29], 2, v147
	s_nop 1
	v_cndmask_b32_e64 v36, v213, v36, s[28:29]
	v_cmp_le_i32_e64 s[28:29], 3, v147
	s_nop 1
	v_cndmask_b32_e64 v37, v213, v37, s[28:29]
	v_cmp_le_i32_e64 s[28:29], 16, v147
	s_nop 1
	v_cndmask_b32_e64 v38, v213, v38, s[28:29]
	v_cmp_le_i32_e64 s[28:29], 17, v147
	s_nop 1
	v_cndmask_b32_e64 v39, v213, v39, s[28:29]
	v_cmp_le_i32_e64 s[28:29], 18, v147
	s_nop 1
	v_cndmask_b32_e64 v40, v213, v40, s[28:29]
	v_cmp_le_i32_e64 s[28:29], 19, v147
	s_nop 1
	v_cndmask_b32_e64 v41, v213, v41, s[28:29]
	v_cmp_le_i32_e64 s[28:29], 32, v147
	s_nop 1
	v_cndmask_b32_e64 v42, v213, v42, s[28:29]
	v_cmp_le_i32_e64 s[28:29], 33, v147
	s_nop 1
	v_cndmask_b32_e64 v43, v213, v43, s[28:29]
	v_cmp_le_i32_e64 s[28:29], 34, v147
	s_nop 1
	v_cndmask_b32_e64 v44, v213, v44, s[28:29]
	v_cmp_le_i32_e64 s[28:29], 35, v147
	s_nop 1
	v_cndmask_b32_e64 v45, v213, v45, s[28:29]
	v_cmp_le_i32_e64 s[28:29], 48, v147
	s_nop 1
	v_cndmask_b32_e64 v46, v213, v46, s[28:29]
	v_cmp_le_i32_e64 s[28:29], 49, v147
	s_nop 1
	v_cndmask_b32_e64 v47, v213, v47, s[28:29]
	v_cmp_le_i32_e64 s[28:29], 50, v147
	s_nop 1
	v_cndmask_b32_e64 v48, v213, v48, s[28:29]
	v_cmp_le_i32_e64 s[28:29], 51, v147
	s_nop 1
	v_cndmask_b32_e64 v49, v213, v49, s[28:29]
.Lsb16_nm1_0:
	v_exp_f32_e32 v34, v34
	v_exp_f32_e32 v35, v35
	v_exp_f32_e32 v36, v36
	v_exp_f32_e32 v37, v37
	v_exp_f32_e32 v38, v38
	v_exp_f32_e32 v39, v39
	v_exp_f32_e32 v40, v40
	v_exp_f32_e32 v41, v41
	v_exp_f32_e32 v42, v42
	v_exp_f32_e32 v43, v43
	v_exp_f32_e32 v44, v44
	v_exp_f32_e32 v45, v45
	v_exp_f32_e32 v46, v46
	v_exp_f32_e32 v47, v47
	v_exp_f32_e32 v48, v48
	v_exp_f32_e32 v49, v49
	v_add_f32_e32 v138, v34, v35
	v_add_f32_e32 v139, v36, v37
	v_add_f32_e32 v140, v38, v39
	v_add_f32_e32 v141, v40, v41
	v_add_f32_e32 v138, v138, v42
	v_add_f32_e32 v139, v139, v43
	v_add_f32_e32 v140, v140, v44
	v_add_f32_e32 v141, v141, v45
	v_add_f32_e32 v138, v138, v46
	v_add_f32_e32 v139, v139, v47
	v_add_f32_e32 v140, v140, v48
	v_add_f32_e32 v141, v141, v49
	v_add_f32_e32 v138, v138, v139
	v_add_f32_e32 v140, v140, v141
	v_add_f32_e32 v138, v138, v140
	v_add_f32_e32 v235, v235, v138
	v_cvt_pk_bf16_f32 v138, v34, v35
	v_cvt_pk_bf16_f32 v139, v36, v37
	v_cvt_pk_bf16_f32 v140, v38, v39
	v_cvt_pk_bf16_f32 v141, v40, v41
	v_cvt_pk_bf16_f32 v142, v42, v43
	v_cvt_pk_bf16_f32 v143, v44, v45
	v_cvt_pk_bf16_f32 v144, v46, v47
	v_cvt_pk_bf16_f32 v145, v48, v49
	ds_read_b128 v[34:37], v234 offset:13824
	ds_read_b128 v[38:41], v234 offset:13888
	ds_read_b128 v[42:45], v234 offset:16128
	ds_read_b128 v[46:49], v234 offset:16192
	s_waitcnt lgkmcnt(7)
	v_mfma_f32_16x16x32_bf16 v[18:21], v[58:61], v[138:141], v[18:21]
	s_waitcnt lgkmcnt(6)
	v_mfma_f32_16x16x32_bf16 v[18:21], v[62:65], v[142:145], v[18:21]
	s_waitcnt lgkmcnt(5)
	v_mfma_f32_16x16x32_bf16 v[22:25], v[50:53], v[138:141], v[22:25]
	s_waitcnt lgkmcnt(4)
	v_mfma_f32_16x16x32_bf16 v[22:25], v[54:57], v[142:145], v[22:25]
	s_waitcnt lgkmcnt(3)
	v_mfma_f32_16x16x32_bf16 v[26:29], v[34:37], v[138:141], v[26:29]
	s_waitcnt lgkmcnt(2)
	v_mfma_f32_16x16x32_bf16 v[26:29], v[38:41], v[142:145], v[26:29]
	s_waitcnt lgkmcnt(1)
	v_mfma_f32_16x16x32_bf16 v[30:33], v[42:45], v[138:141], v[30:33]
	s_waitcnt lgkmcnt(0)
	v_mfma_f32_16x16x32_bf16 v[30:33], v[46:49], v[142:145], v[30:33]

.Lsb16_nost_1:
	s_and_b32 s38, s25, 63
	v_readlane_b32 s32, v136, s38
	v_readlane_b32 s38, v137, s38
	s_bitcmp1_b32 s25, 6
	s_cselect_b32 s77, s38, s32
	s_and_b32 s56, s77, s86
	s_and_b32 s57, s77, s87
	s_or_b32 s28, s56, s57
	s_cmp_eq_u32 s28, 0
	s_cbranch_scc1 .Lsb16_end_1
	s_and_b32 s38, s25, 63
	v_readlane_b32 s32, v133, s38
	v_readlane_b32 s38, v148, s38
	s_bitcmp1_b32 s25, 6
	s_cselect_b32 s76, s38, s32
	s_lshl_b32 s83, s76, 6
	v_subrev_u32_e32 v147, s83, v239
	s_cmp_eq_u32 s56, 0
	s_cbranch_scc1 .Lsb16_g1_1
	ds_read_b128 v[50:53], v234 offset:18432
	ds_read_b128 v[54:57], v234 offset:18496
	ds_read_b128 v[58:61], v234 offset:20736
	ds_read_b128 v[62:65], v234 offset:20800
	ds_read_b128 v[138:141], v234 offset:23040
	ds_read_b128 v[142:145], v234 offset:23104
	v_subrev_u32_e32 v146, s94, v236
	v_lshrrev_b32_e64 v146, v146, s77
	v_and_b32_e32 v146, 1, v146
	v_cmp_ne_u32_e32 vcc, 0, v146
	s_nop 1
	v_cndmask_b32_e32 v146, v213, v100, vcc
	s_waitcnt lgkmcnt(5)
	v_mfma_f32_16x16x32_bf16 v[34:37], v[50:53], v[66:69], 0
	s_waitcnt lgkmcnt(4)
	v_mfma_f32_16x16x32_bf16 v[34:37], v[54:57], v[70:73], v[34:37]
	ds_read_b128 v[50:53], v234 offset:25344
	ds_read_b128 v[54:57], v234 offset:25408
	s_waitcnt lgkmcnt(5)
	v_mfma_f32_16x16x32_bf16 v[38:41], v[58:61], v[66:69], 0
	s_waitcnt lgkmcnt(4)
	v_mfma_f32_16x16x32_bf16 v[38:41], v[62:65], v[70:73], v[38:41]
	ds_read_b128 v[58:61], v234 offset:27648
	ds_read_b128 v[62:65], v234 offset:27712
	s_waitcnt lgkmcnt(5)
	v_mfma_f32_16x16x32_bf16 v[42:45], v[138:141], v[66:69], 0
	s_waitcnt lgkmcnt(4)
	v_mfma_f32_16x16x32_bf16 v[42:45], v[142:145], v[70:73], v[42:45]
	s_waitcnt lgkmcnt(3)
	v_mfma_f32_16x16x32_bf16 v[46:49], v[50:53], v[66:69], 0
	s_waitcnt lgkmcnt(2)
	v_mfma_f32_16x16x32_bf16 v[46:49], v[54:57], v[70:73], v[46:49]
	ds_read_b128 v[50:53], v234 offset:29952
	ds_read_b128 v[54:57], v234 offset:30016
	v_fma_f32 v34, v34, s48, v146
	v_fma_f32 v35, v35, s48, v146
	v_fma_f32 v36, v36, s48, v146
	v_fma_f32 v37, v37, s48, v146
	v_fma_f32 v38, v38, s48, v146
	v_fma_f32 v39, v39, s48, v146
	v_fma_f32 v40, v40, s48, v146
	v_fma_f32 v41, v41, s48, v146
	v_fma_f32 v42, v42, s48, v146
	v_fma_f32 v43, v43, s48, v146
	v_fma_f32 v44, v44, s48, v146
	v_fma_f32 v45, v45, s48, v146
	v_fma_f32 v46, v46, s48, v146
	v_fma_f32 v47, v47, s48, v146
	v_fma_f32 v48, v48, s48, v146
	v_fma_f32 v49, v49, s48, v146
	s_cmp_lg_u32 s76, s72
	s_cbranch_scc1 .Lsb16_nm0_1
	v_cmp_le_i32_e64 s[28:29], 0, v147
	s_nop 1
	v_cndmask_b32_e64 v34, v213, v34, s[28:29]
	v_cmp_le_i32_e64 s[28:29], 1, v147
	s_nop 1
	v_cndmask_b32_e64 v35, v213, v35, s[28:29]
	v_cmp_le_i32_e64 s[28:29], 2, v147
	s_nop 1
	v_cndmask_b32_e64 v36, v213, v36, s[28:29]
	v_cmp_le_i32_e64 s[28:29], 3, v147
	s_nop 1
	v_cndmask_b32_e64 v37, v213, v37, s[28:29]
	v_cmp_le_i32_e64 s[28:29], 16, v147
	s_nop 1
	v_cndmask_b32_e64 v38, v213, v38, s[28:29]
	v_cmp_le_i32_e64 s[28:29], 17, v147
	s_nop 1
	v_cndmask_b32_e64 v39, v213, v39, s[28:29]
	v_cmp_le_i32_e64 s[28:29], 18, v147
	s_nop 1
	v_cndmask_b32_e64 v40, v213, v40, s[28:29]
	v_cmp_le_i32_e64 s[28:29], 19, v147
	s_nop 1
	v_cndmask_b32_e64 v41, v213, v41, s[28:29]
	v_cmp_le_i32_e64 s[28:29], 32, v147
	s_nop 1
	v_cndmask_b32_e64 v42, v213, v42, s[28:29]
	v_cmp_le_i32_e64 s[28:29], 33, v147
	s_nop 1
	v_cndmask_b32_e64 v43, v213, v43, s[28:29]
	v_cmp_le_i32_e64 s[28:29], 34, v147
	s_nop 1
	v_cndmask_b32_e64 v44, v213, v44, s[28:29]
	v_cmp_le_i32_e64 s[28:29], 35, v147
	s_nop 1
	v_cndmask_b32_e64 v45, v213, v45, s[28:29]
	v_cmp_le_i32_e64 s[28:29], 48, v147
	s_nop 1
	v_cndmask_b32_e64 v46, v213, v46, s[28:29]
	v_cmp_le_i32_e64 s[28:29], 49, v147
	s_nop 1
	v_cndmask_b32_e64 v47, v213, v47, s[28:29]
	v_cmp_le_i32_e64 s[28:29], 50, v147
	s_nop 1
	v_cndmask_b32_e64 v48, v213, v48, s[28:29]
	v_cmp_le_i32_e64 s[28:29], 51, v147
	s_nop 1
	v_cndmask_b32_e64 v49, v213, v49, s[28:29]
.Lsb16_nm0_1:
	v_exp_f32_e32 v34, v34
	v_exp_f32_e32 v35, v35
	v_exp_f32_e32 v36, v36
	v_exp_f32_e32 v37, v37
	v_exp_f32_e32 v38, v38
	v_exp_f32_e32 v39, v39
	v_exp_f32_e32 v40, v40
	v_exp_f32_e32 v41, v41
	v_exp_f32_e32 v42, v42
	v_exp_f32_e32 v43, v43
	v_exp_f32_e32 v44, v44
	v_exp_f32_e32 v45, v45
	v_exp_f32_e32 v46, v46
	v_exp_f32_e32 v47, v47
	v_exp_f32_e32 v48, v48
	v_exp_f32_e32 v49, v49
	v_add_f32_e32 v138, v34, v35
	v_add_f32_e32 v139, v36, v37
	v_add_f32_e32 v140, v38, v39
	v_add_f32_e32 v141, v40, v41
	v_add_f32_e32 v138, v138, v42
	v_add_f32_e32 v139, v139, v43
	v_add_f32_e32 v140, v140, v44
	v_add_f32_e32 v141, v141, v45
	v_add_f32_e32 v138, v138, v46
	v_add_f32_e32 v139, v139, v47
	v_add_f32_e32 v140, v140, v48
	v_add_f32_e32 v141, v141, v49
	v_add_f32_e32 v138, v138, v139
	v_add_f32_e32 v140, v140, v141
	v_add_f32_e32 v138, v138, v140
	v_add_f32_e32 v129, v129, v138
	v_cvt_pk_bf16_f32 v138, v34, v35
	v_cvt_pk_bf16_f32 v139, v36, v37
	v_cvt_pk_bf16_f32 v140, v38, v39
	v_cvt_pk_bf16_f32 v141, v40, v41
	v_cvt_pk_bf16_f32 v142, v42, v43
	v_cvt_pk_bf16_f32 v143, v44, v45
	v_cvt_pk_bf16_f32 v144, v46, v47
	v_cvt_pk_bf16_f32 v145, v48, v49
	ds_read_b128 v[34:37], v234 offset:32256
	ds_read_b128 v[38:41], v234 offset:32320
	ds_read_b128 v[42:45], v234 offset:34560
	ds_read_b128 v[46:49], v234 offset:34624
	s_waitcnt lgkmcnt(7)
	v_mfma_f32_16x16x32_bf16 v[2:5], v[58:61], v[138:141], v[2:5]
	s_waitcnt lgkmcnt(6)
	v_mfma_f32_16x16x32_bf16 v[2:5], v[62:65], v[142:145], v[2:5]
	s_waitcnt lgkmcnt(5)
	v_mfma_f32_16x16x32_bf16 v[6:9], v[50:53], v[138:141], v[6:9]
	s_waitcnt lgkmcnt(4)
	v_mfma_f32_16x16x32_bf16 v[6:9], v[54:57], v[142:145], v[6:9]
	s_waitcnt lgkmcnt(3)
	v_mfma_f32_16x16x32_bf16 v[10:13], v[34:37], v[138:141], v[10:13]
	s_waitcnt lgkmcnt(2)
	v_mfma_f32_16x16x32_bf16 v[10:13], v[38:41], v[142:145], v[10:13]
	s_waitcnt lgkmcnt(1)
	v_mfma_f32_16x16x32_bf16 v[14:17], v[42:45], v[138:141], v[14:17]
	s_waitcnt lgkmcnt(0)
	v_mfma_f32_16x16x32_bf16 v[14:17], v[46:49], v[142:145], v[14:17]
.Lsb16_g1_1:
	s_cmp_eq_u32 s57, 0
	s_cbranch_scc1 .Lsb16_end_1
	ds_read_b128 v[50:53], v234 offset:18432
	ds_read_b128 v[54:57], v234 offset:18496
	ds_read_b128 v[58:61], v234 offset:20736
	ds_read_b128 v[62:65], v234 offset:20800
	ds_read_b128 v[138:141], v234 offset:23040
	ds_read_b128 v[142:145], v234 offset:23104
	v_add_u32_e32 v147, 2, v147
	v_subrev_u32_e32 v146, s94, v236
	v_add_u32_e32 v146, 2, v146
	v_lshrrev_b32_e64 v146, v146, s77
	v_and_b32_e32 v146, 1, v146
	v_cmp_ne_u32_e32 vcc, 0, v146
	s_nop 1
	v_cndmask_b32_e32 v146, v213, v100, vcc
	s_waitcnt lgkmcnt(5)
	v_mfma_f32_16x16x32_bf16 v[34:37], v[50:53], v[74:77], 0
	s_waitcnt lgkmcnt(4)
	v_mfma_f32_16x16x32_bf16 v[34:37], v[54:57], v[78:81], v[34:37]
	ds_read_b128 v[50:53], v234 offset:25344
	ds_read_b128 v[54:57], v234 offset:25408
	s_waitcnt lgkmcnt(5)
	v_mfma_f32_16x16x32_bf16 v[38:41], v[58:61], v[74:77], 0
	s_waitcnt lgkmcnt(4)
	v_mfma_f32_16x16x32_bf16 v[38:41], v[62:65], v[78:81], v[38:41]
	ds_read_b128 v[58:61], v234 offset:27648
	ds_read_b128 v[62:65], v234 offset:27712
	s_waitcnt lgkmcnt(5)
	v_mfma_f32_16x16x32_bf16 v[42:45], v[138:141], v[74:77], 0
	s_waitcnt lgkmcnt(4)
	v_mfma_f32_16x16x32_bf16 v[42:45], v[142:145], v[78:81], v[42:45]
	s_waitcnt lgkmcnt(3)
	v_mfma_f32_16x16x32_bf16 v[46:49], v[50:53], v[74:77], 0
	s_waitcnt lgkmcnt(2)
	v_mfma_f32_16x16x32_bf16 v[46:49], v[54:57], v[78:81], v[46:49]
	ds_read_b128 v[50:53], v234 offset:29952
	ds_read_b128 v[54:57], v234 offset:30016
	v_fma_f32 v34, v34, s48, v146
	v_fma_f32 v35, v35, s48, v146
	v_fma_f32 v36, v36, s48, v146
	v_fma_f32 v37, v37, s48, v146
	v_fma_f32 v38, v38, s48, v146
	v_fma_f32 v39, v39, s48, v146
	v_fma_f32 v40, v40, s48, v146
	v_fma_f32 v41, v41, s48, v146
	v_fma_f32 v42, v42, s48, v146
	v_fma_f32 v43, v43, s48, v146
	v_fma_f32 v44, v44, s48, v146
	v_fma_f32 v45, v45, s48, v146
	v_fma_f32 v46, v46, s48, v146
	v_fma_f32 v47, v47, s48, v146
	v_fma_f32 v48, v48, s48, v146
	v_fma_f32 v49, v49, s48, v146
	s_cmp_lg_u32 s76, s72
	s_cbranch_scc1 .Lsb16_nm1_1
	v_cmp_le_i32_e64 s[28:29], 0, v147
	s_nop 1
	v_cndmask_b32_e64 v34, v213, v34, s[28:29]
	v_cmp_le_i32_e64 s[28:29], 1, v147
	s_nop 1
	v_cndmask_b32_e64 v35, v213, v35, s[28:29]
	v_cmp_le_i32_e64 s[28:29], 2, v147
	s_nop 1
	v_cndmask_b32_e64 v36, v213, v36, s[28:29]
	v_cmp_le_i32_e64 s[28:29], 3, v147
	s_nop 1
	v_cndmask_b32_e64 v37, v213, v37, s[28:29]
	v_cmp_le_i32_e64 s[28:29], 16, v147
	s_nop 1
	v_cndmask_b32_e64 v38, v213, v38, s[28:29]
	v_cmp_le_i32_e64 s[28:29], 17, v147
	s_nop 1
	v_cndmask_b32_e64 v39, v213, v39, s[28:29]
	v_cmp_le_i32_e64 s[28:29], 18, v147
	s_nop 1
	v_cndmask_b32_e64 v40, v213, v40, s[28:29]
	v_cmp_le_i32_e64 s[28:29], 19, v147
	s_nop 1
	v_cndmask_b32_e64 v41, v213, v41, s[28:29]
	v_cmp_le_i32_e64 s[28:29], 32, v147
	s_nop 1
	v_cndmask_b32_e64 v42, v213, v42, s[28:29]
	v_cmp_le_i32_e64 s[28:29], 33, v147
	s_nop 1
	v_cndmask_b32_e64 v43, v213, v43, s[28:29]
	v_cmp_le_i32_e64 s[28:29], 34, v147
	s_nop 1
	v_cndmask_b32_e64 v44, v213, v44, s[28:29]
	v_cmp_le_i32_e64 s[28:29], 35, v147
	s_nop 1
	v_cndmask_b32_e64 v45, v213, v45, s[28:29]
	v_cmp_le_i32_e64 s[28:29], 48, v147
	s_nop 1
	v_cndmask_b32_e64 v46, v213, v46, s[28:29]
	v_cmp_le_i32_e64 s[28:29], 49, v147
	s_nop 1
	v_cndmask_b32_e64 v47, v213, v47, s[28:29]
	v_cmp_le_i32_e64 s[28:29], 50, v147
	s_nop 1
	v_cndmask_b32_e64 v48, v213, v48, s[28:29]
	v_cmp_le_i32_e64 s[28:29], 51, v147
	s_nop 1
	v_cndmask_b32_e64 v49, v213, v49, s[28:29]
.Lsb16_nm1_1:
	v_exp_f32_e32 v34, v34
	v_exp_f32_e32 v35, v35
	v_exp_f32_e32 v36, v36
	v_exp_f32_e32 v37, v37
	v_exp_f32_e32 v38, v38
	v_exp_f32_e32 v39, v39
	v_exp_f32_e32 v40, v40
	v_exp_f32_e32 v41, v41
	v_exp_f32_e32 v42, v42
	v_exp_f32_e32 v43, v43
	v_exp_f32_e32 v44, v44
	v_exp_f32_e32 v45, v45
	v_exp_f32_e32 v46, v46
	v_exp_f32_e32 v47, v47
	v_exp_f32_e32 v48, v48
	v_exp_f32_e32 v49, v49
	v_add_f32_e32 v138, v34, v35
	v_add_f32_e32 v139, v36, v37
	v_add_f32_e32 v140, v38, v39
	v_add_f32_e32 v141, v40, v41
	v_add_f32_e32 v138, v138, v42
	v_add_f32_e32 v139, v139, v43
	v_add_f32_e32 v140, v140, v44
	v_add_f32_e32 v141, v141, v45
	v_add_f32_e32 v138, v138, v46
	v_add_f32_e32 v139, v139, v47
	v_add_f32_e32 v140, v140, v48
	v_add_f32_e32 v141, v141, v49
	v_add_f32_e32 v138, v138, v139
	v_add_f32_e32 v140, v140, v141
	v_add_f32_e32 v138, v138, v140
	v_add_f32_e32 v235, v235, v138
	v_cvt_pk_bf16_f32 v138, v34, v35
	v_cvt_pk_bf16_f32 v139, v36, v37
	v_cvt_pk_bf16_f32 v140, v38, v39
	v_cvt_pk_bf16_f32 v141, v40, v41
	v_cvt_pk_bf16_f32 v142, v42, v43
	v_cvt_pk_bf16_f32 v143, v44, v45
	v_cvt_pk_bf16_f32 v144, v46, v47
	v_cvt_pk_bf16_f32 v145, v48, v49
	ds_read_b128 v[34:37], v234 offset:32256
	ds_read_b128 v[38:41], v234 offset:32320
	ds_read_b128 v[42:45], v234 offset:34560
	ds_read_b128 v[46:49], v234 offset:34624
	s_waitcnt lgkmcnt(7)
	v_mfma_f32_16x16x32_bf16 v[18:21], v[58:61], v[138:141], v[18:21]
	s_waitcnt lgkmcnt(6)
	v_mfma_f32_16x16x32_bf16 v[18:21], v[62:65], v[142:145], v[18:21]
	s_waitcnt lgkmcnt(5)
	v_mfma_f32_16x16x32_bf16 v[22:25], v[50:53], v[138:141], v[22:25]
	s_waitcnt lgkmcnt(4)
	v_mfma_f32_16x16x32_bf16 v[22:25], v[54:57], v[142:145], v[22:25]
	s_waitcnt lgkmcnt(3)
	v_mfma_f32_16x16x32_bf16 v[26:29], v[34:37], v[138:141], v[26:29]
	s_waitcnt lgkmcnt(2)
	v_mfma_f32_16x16x32_bf16 v[26:29], v[38:41], v[142:145], v[26:29]
	s_waitcnt lgkmcnt(1)
	v_mfma_f32_16x16x32_bf16 v[30:33], v[42:45], v[138:141], v[30:33]
	s_waitcnt lgkmcnt(0)
	v_mfma_f32_16x16x32_bf16 v[30:33], v[46:49], v[142:145], v[30:33]
